# panel exchange: dropped L1 invalidate after counter poll (exchanged partials are read with agent-scope sc1 loads)
# speedup vs baseline: 1.0104x; 1.0104x over previous
;     __device__ __forceinline__ void exchange(int e, float (&sv)[2][4], float (&rv)[2][4], const Unit& u, int wr, int wc, int fr, int fq, LAS unsigned char* lds, int wid, int lane) const {
;     ...
;         if (wid == 0) {
;             unsigned sp = 0;
;             while ((unsigned)__builtin_amdgcn_readfirstlane(__hip_atomic_load(cnt, __ATOMIC_RELAXED, __HIP_MEMORY_SCOPE_AGENT)) < 16u) { __builtin_amdgcn_s_sleep(2); if (++sp > (1u << 22)) break; }
;             __builtin_amdgcn_fence(__ATOMIC_ACQUIRE, "agent");
;         }
;         asm volatile("s_waitcnt vmcnt(0) lgkmcnt(0)" ::: "memory"); __builtin_amdgcn_s_barrier(); asm volatile("" ::: "memory");
;         if (tid < 256) {
;             const float* sl = xbuf + ((size_t)u.pm * 256 + tid) * 4;
;             const float t0 = __hip_atomic_load(sl + 0, __ATOMIC_RELAXED, __HIP_MEMORY_SCOPE_AGENT), t1 = __hip_atomic_load(sl + 1, __ATOMIC_RELAXED, __HIP_MEMORY_SCOPE_AGENT);
;             const float t2 = __hip_atomic_load(sl + 2, __ATOMIC_RELAXED, __HIP_MEMORY_SCOPE_AGENT), t3 = __hip_atomic_load(sl + 3, __ATOMIC_RELAXED, __HIP_MEMORY_SCOPE_AGENT);
;             Sx[tid] = 1.0f / sqrtf(((t0 + t1) + (t2 + t3)) * (1.0f / 1024.0f) + RMS_EPS);
;         }
.LBB0_1431:
	s_waitcnt lgkmcnt(0)
.LBB0_1432:
	s_waitcnt vmcnt(0) lgkmcnt(0)
	s_barrier
	s_and_saveexec_b64 s[42:43], s[6:7]
	s_cbranch_execz .LBB0_1434
	s_lshl_b64 s[10:11], s[28:29], 12
	v_lshl_add_u64 v[146:147], v[138:139], 0, s[10:11]
	global_load_dword v148, v[146:147], off sc1
	global_load_dword v150, v[146:147], off offset:4 sc1
	global_load_dword v149, v[146:147], off offset:8 sc1
	global_load_dword v151, v[146:147], off offset:12 sc1
	s_mov_b32 s10, 0xf800000
	s_waitcnt vmcnt(0)
	v_pk_add_f32 v[146:147], v[148:149], v[150:151]
	s_nop 0
	v_add_f32_e32 v146, v146, v147
	v_fmamk_f32 v146, v146, 0x3a800000, v228
	v_mul_f32_e32 v147, 0x4f800000, v146
	v_cmp_gt_f32_e32 vcc, s10, v146
	s_nop 1
	v_cndmask_b32_e32 v146, v146, v147, vcc
	v_sqrt_f32_e32 v147, v146
	s_nop 0
	v_add_u32_e32 v148, -1, v147
	v_add_u32_e32 v149, 1, v147
	v_fma_f32 v150, -v148, v147, v146
	v_fma_f32 v151, -v149, v147, v146
	v_cmp_ge_f32_e64 s[10:11], 0, v150
	s_nop 1
	v_cndmask_b32_e64 v147, v147, v148, s[10:11]
	v_cmp_lt_f32_e64 s[10:11], 0, v151
	s_nop 1
	v_cndmask_b32_e64 v147, v147, v149, s[10:11]
	v_mul_f32_e32 v148, 0x37800000, v147
	v_cndmask_b32_e32 v147, v147, v148, vcc
	v_cmp_class_f32_e32 vcc, v146, v227
	s_nop 1
	v_cndmask_b32_e32 v146, v147, v146, vcc
	v_div_scale_f32 v147, s[10:11], v146, v146, 1.0
	v_rcp_f32_e32 v148, v147
	v_div_scale_f32 v149, vcc, 1.0, v146, 1.0
	v_fma_f32 v150, -v147, v148, 1.0
	v_fmac_f32_e32 v148, v150, v148
	v_mul_f32_e32 v150, v149, v148
	v_fma_f32 v151, -v147, v150, v149
	v_fmac_f32_e32 v150, v151, v148
	v_fma_f32 v147, -v147, v150, v149
	v_div_fmas_f32 v147, v147, v148, v150
	v_div_fixup_f32 v146, v147, v146, 1.0
	ds_write_b32 v209, v146

;     __device__ __forceinline__ void exchange(int e, float (&sv)[2][4], float (&rv)[2][4], const Unit& u, int wr, int wc, int fr, int fq, LAS unsigned char* lds, int wid, int lane) const {
;     ...
;         if (wid == 0) {
;             unsigned sp = 0;
;             while ((unsigned)__builtin_amdgcn_readfirstlane(__hip_atomic_load(cnt, __ATOMIC_RELAXED, __HIP_MEMORY_SCOPE_AGENT)) < 16u) { __builtin_amdgcn_s_sleep(2); if (++sp > (1u << 22)) break; }
;             __builtin_amdgcn_fence(__ATOMIC_ACQUIRE, "agent");
;         }
;         asm volatile("s_waitcnt vmcnt(0) lgkmcnt(0)" ::: "memory"); __builtin_amdgcn_s_barrier(); asm volatile("" ::: "memory");
;         if (tid < 256) {
;             const float* sl = xbuf + ((size_t)u.pm * 256 + tid) * 4;
;             const float t0 = __hip_atomic_load(sl + 0, __ATOMIC_RELAXED, __HIP_MEMORY_SCOPE_AGENT), t1 = __hip_atomic_load(sl + 1, __ATOMIC_RELAXED, __HIP_MEMORY_SCOPE_AGENT);
;             const float t2 = __hip_atomic_load(sl + 2, __ATOMIC_RELAXED, __HIP_MEMORY_SCOPE_AGENT), t3 = __hip_atomic_load(sl + 3, __ATOMIC_RELAXED, __HIP_MEMORY_SCOPE_AGENT);
;             Sx[tid] = 1.0f / sqrtf(((t0 + t1) + (t2 + t3)) * (1.0f / 1024.0f) + RMS_EPS);
;         }
.LBB0_1464:
	s_waitcnt lgkmcnt(0)
.LBB0_1465:
	s_waitcnt vmcnt(0) lgkmcnt(0)
	s_barrier
	s_and_saveexec_b64 s[10:11], s[6:7]
	s_cbranch_execz .LBB0_1467
	s_lshl_b64 s[8:9], s[28:29], 12
	v_lshl_add_u64 v[18:19], v[140:141], 0, s[8:9]
	global_load_dword v20, v[18:19], off sc1
	global_load_dword v22, v[18:19], off offset:4 sc1
	global_load_dword v21, v[18:19], off offset:8 sc1
	global_load_dword v23, v[18:19], off offset:12 sc1
	s_mov_b32 s8, 0xf800000
	s_waitcnt vmcnt(0)
	v_pk_add_f32 v[18:19], v[20:21], v[22:23]
	s_nop 0
	v_add_f32_e32 v18, v18, v19
	v_fmamk_f32 v18, v18, 0x3a800000, v228
	v_mul_f32_e32 v19, 0x4f800000, v18
	v_cmp_gt_f32_e32 vcc, s8, v18
	s_nop 1
	v_cndmask_b32_e32 v18, v18, v19, vcc
	v_sqrt_f32_e32 v19, v18
	s_nop 0
	v_add_u32_e32 v20, -1, v19
	v_add_u32_e32 v21, 1, v19
	v_fma_f32 v22, -v20, v19, v18
	v_fma_f32 v23, -v21, v19, v18
	v_cmp_ge_f32_e64 s[8:9], 0, v22
	s_nop 1
	v_cndmask_b32_e64 v19, v19, v20, s[8:9]
	v_cmp_lt_f32_e64 s[8:9], 0, v23
	s_nop 1
	v_cndmask_b32_e64 v19, v19, v21, s[8:9]
	v_mul_f32_e32 v20, 0x37800000, v19
	v_cndmask_b32_e32 v19, v19, v20, vcc
	v_cmp_class_f32_e32 vcc, v18, v227
	s_nop 1
	v_cndmask_b32_e32 v18, v19, v18, vcc
	v_div_scale_f32 v19, s[8:9], v18, v18, 1.0
	v_rcp_f32_e32 v20, v19
	v_div_scale_f32 v21, vcc, 1.0, v18, 1.0
	v_fma_f32 v22, -v19, v20, 1.0
	v_fmac_f32_e32 v20, v22, v20
	v_mul_f32_e32 v22, v21, v20
	v_fma_f32 v23, -v19, v22, v21
	v_fmac_f32_e32 v22, v23, v20
	v_fma_f32 v19, -v19, v22, v21
	v_div_fmas_f32 v19, v19, v20, v22
	v_div_fixup_f32 v18, v19, v18, 1.0
	ds_write_b32 v209, v18

;     __device__ __forceinline__ void exchange(int e, float (&sv)[2][4], float (&rv)[2][4], const Unit& u, int wr, int wc, int fr, int fq, LAS unsigned char* lds, int wid, int lane) const {
;     ...
;         if (wid == 0) {
;             unsigned sp = 0;
;             while ((unsigned)__builtin_amdgcn_readfirstlane(__hip_atomic_load(cnt, __ATOMIC_RELAXED, __HIP_MEMORY_SCOPE_AGENT)) < 16u) { __builtin_amdgcn_s_sleep(2); if (++sp > (1u << 22)) break; }
;             __builtin_amdgcn_fence(__ATOMIC_ACQUIRE, "agent");
;         }
;         asm volatile("s_waitcnt vmcnt(0) lgkmcnt(0)" ::: "memory"); __builtin_amdgcn_s_barrier(); asm volatile("" ::: "memory");
;         if (tid < 256) {
;             const float* sl = xbuf + ((size_t)u.pm * 256 + tid) * 4;
;             const float t0 = __hip_atomic_load(sl + 0, __ATOMIC_RELAXED, __HIP_MEMORY_SCOPE_AGENT), t1 = __hip_atomic_load(sl + 1, __ATOMIC_RELAXED, __HIP_MEMORY_SCOPE_AGENT);
;             const float t2 = __hip_atomic_load(sl + 2, __ATOMIC_RELAXED, __HIP_MEMORY_SCOPE_AGENT), t3 = __hip_atomic_load(sl + 3, __ATOMIC_RELAXED, __HIP_MEMORY_SCOPE_AGENT);
;             Sx[tid] = 1.0f / sqrtf(((t0 + t1) + (t2 + t3)) * (1.0f / 1024.0f) + RMS_EPS);
;         }
.LBB0_1665:
	s_waitcnt lgkmcnt(0)
.LBB0_1666:
	s_waitcnt vmcnt(0) lgkmcnt(0)
	s_barrier
	s_and_saveexec_b64 s[44:45], s[6:7]
	s_cbranch_execz .LBB0_1668
	s_lshl_b64 s[10:11], s[36:37], 12
	v_lshl_add_u64 v[146:147], v[138:139], 0, s[10:11]
	global_load_dword v148, v[146:147], off sc1
	global_load_dword v150, v[146:147], off offset:4 sc1
	global_load_dword v149, v[146:147], off offset:8 sc1
	global_load_dword v151, v[146:147], off offset:12 sc1
	s_mov_b32 s10, 0xf800000
	s_waitcnt vmcnt(0)
	v_pk_add_f32 v[146:147], v[148:149], v[150:151]
	s_nop 0
	v_add_f32_e32 v146, v146, v147
	v_fmamk_f32 v146, v146, 0x3a800000, v228
	v_mul_f32_e32 v147, 0x4f800000, v146
	v_cmp_gt_f32_e32 vcc, s10, v146
	s_nop 1
	v_cndmask_b32_e32 v146, v146, v147, vcc
	v_sqrt_f32_e32 v147, v146
	s_nop 0
	v_add_u32_e32 v148, -1, v147
	v_add_u32_e32 v149, 1, v147
	v_fma_f32 v150, -v148, v147, v146
	v_fma_f32 v151, -v149, v147, v146
	v_cmp_ge_f32_e64 s[10:11], 0, v150
	s_nop 1
	v_cndmask_b32_e64 v147, v147, v148, s[10:11]
	v_cmp_lt_f32_e64 s[10:11], 0, v151
	s_nop 1
	v_cndmask_b32_e64 v147, v147, v149, s[10:11]
	v_mul_f32_e32 v148, 0x37800000, v147
	v_cndmask_b32_e32 v147, v147, v148, vcc
	v_cmp_class_f32_e32 vcc, v146, v227
	s_nop 1
	v_cndmask_b32_e32 v146, v147, v146, vcc
	v_div_scale_f32 v147, s[10:11], v146, v146, 1.0
	v_rcp_f32_e32 v148, v147
	v_div_scale_f32 v149, vcc, 1.0, v146, 1.0
	v_fma_f32 v150, -v147, v148, 1.0
	v_fmac_f32_e32 v148, v150, v148
	v_mul_f32_e32 v150, v149, v148
	v_fma_f32 v151, -v147, v150, v149
	v_fmac_f32_e32 v150, v151, v148
	v_fma_f32 v147, -v147, v150, v149
	v_div_fmas_f32 v147, v147, v148, v150
	v_div_fixup_f32 v146, v147, v146, 1.0
	ds_write_b32 v190, v146

;     __device__ __forceinline__ void exchange(int e, float (&sv)[2][4], float (&rv)[2][4], const Unit& u, int wr, int wc, int fr, int fq, LAS unsigned char* lds, int wid, int lane) const {
;     ...
;         if (wid == 0) {
;             unsigned sp = 0;
;             while ((unsigned)__builtin_amdgcn_readfirstlane(__hip_atomic_load(cnt, __ATOMIC_RELAXED, __HIP_MEMORY_SCOPE_AGENT)) < 16u) { __builtin_amdgcn_s_sleep(2); if (++sp > (1u << 22)) break; }
;             __builtin_amdgcn_fence(__ATOMIC_ACQUIRE, "agent");
;         }
;         asm volatile("s_waitcnt vmcnt(0) lgkmcnt(0)" ::: "memory"); __builtin_amdgcn_s_barrier(); asm volatile("" ::: "memory");
;         if (tid < 256) {
;             const float* sl = xbuf + ((size_t)u.pm * 256 + tid) * 4;
;             const float t0 = __hip_atomic_load(sl + 0, __ATOMIC_RELAXED, __HIP_MEMORY_SCOPE_AGENT), t1 = __hip_atomic_load(sl + 1, __ATOMIC_RELAXED, __HIP_MEMORY_SCOPE_AGENT);
;             const float t2 = __hip_atomic_load(sl + 2, __ATOMIC_RELAXED, __HIP_MEMORY_SCOPE_AGENT), t3 = __hip_atomic_load(sl + 3, __ATOMIC_RELAXED, __HIP_MEMORY_SCOPE_AGENT);
;             Sx[tid] = 1.0f / sqrtf(((t0 + t1) + (t2 + t3)) * (1.0f / 1024.0f) + RMS_EPS);
;         }
.LBB0_1702:
	s_waitcnt lgkmcnt(0)
.LBB0_1703:
	s_waitcnt vmcnt(0) lgkmcnt(0)
	s_barrier
	s_and_saveexec_b64 s[10:11], s[6:7]
	s_cbranch_execz .LBB0_1705
	s_lshl_b64 s[8:9], s[36:37], 12
	v_lshl_add_u64 v[154:155], v[140:141], 0, s[8:9]
	global_load_dword v156, v[154:155], off sc1
	global_load_dword v158, v[154:155], off offset:4 sc1
	global_load_dword v157, v[154:155], off offset:8 sc1
	global_load_dword v159, v[154:155], off offset:12 sc1
	s_mov_b32 s8, 0xf800000
	s_waitcnt vmcnt(0)
	v_pk_add_f32 v[154:155], v[156:157], v[158:159]
	s_nop 0
	v_add_f32_e32 v154, v154, v155
	v_fmamk_f32 v154, v154, 0x3a800000, v228
	v_mul_f32_e32 v155, 0x4f800000, v154
	v_cmp_gt_f32_e32 vcc, s8, v154
	s_nop 1
	v_cndmask_b32_e32 v154, v154, v155, vcc
	v_sqrt_f32_e32 v155, v154
	s_nop 0
	v_add_u32_e32 v156, -1, v155
	v_add_u32_e32 v157, 1, v155
	v_fma_f32 v158, -v156, v155, v154
	v_fma_f32 v159, -v157, v155, v154
	v_cmp_ge_f32_e64 s[8:9], 0, v158
	s_nop 1
	v_cndmask_b32_e64 v155, v155, v156, s[8:9]
	v_cmp_lt_f32_e64 s[8:9], 0, v159
	s_nop 1
	v_cndmask_b32_e64 v155, v155, v157, s[8:9]
	v_mul_f32_e32 v156, 0x37800000, v155
	v_cndmask_b32_e32 v155, v155, v156, vcc
	v_cmp_class_f32_e32 vcc, v154, v227
	s_nop 1
	v_cndmask_b32_e32 v154, v155, v154, vcc
	v_div_scale_f32 v155, s[8:9], v154, v154, 1.0
	v_rcp_f32_e32 v156, v155
	v_div_scale_f32 v157, vcc, 1.0, v154, 1.0
	v_fma_f32 v158, -v155, v156, 1.0
	v_fmac_f32_e32 v156, v158, v156
	v_mul_f32_e32 v158, v157, v156
	v_fma_f32 v159, -v155, v158, v157
	v_fmac_f32_e32 v158, v159, v156
	v_fma_f32 v155, -v155, v158, v157
	v_div_fmas_f32 v155, v155, v156, v158
	v_div_fixup_f32 v154, v155, v154, 1.0
	ds_write_b32 v190, v154
